# sample_gemm all 8 phases: coalesced global loads via wave-private swizzled LDS staging (K=2816: 11 chunks, 4 in flight)
# speedup vs baseline: 1.0703x; 1.0113x over previous
; template <class EpiS>
; DI void sample_gemm(LAS unsigned char* lds, const bf16_t* A, const bf16_t* Bt, int nN, int K, const EpiS& E) {
;     const int tid = threadIdx.x, lane = tid & 63, w = __builtin_amdgcn_readfirstlane(tid >> 6), r32 = lane & 31, h = lane >> 5;
;     const int nunits = 16 * nN, kw = K >> 3, nk = kw >> 4;
;     for (int un = (int)blockIdx.x; un < nunits; un += (int)gridDim.x) {
;         const int rb = un & 3, wc = (un >> 2) & 3, pn = un >> 4;
;         const bf16_t* ap = A + (size_t)(MP + rb * 32 + r32) * K + w * kw + h * 8;
;         const bf16_t* b0p = Bt + (size_t)(pn * 256 + wc * 32 + r32) * K + w * kw + h * 8;
;         const bf16_t* b1p = b0p + (size_t)128 * K;
;         f32x16 c0, c1;
; #pragma unroll
;         for (int r = 0; r < 16; ++r) { c0[r] = 0.f; c1[r] = 0.f; }
.LBB0_719:
	s_cmp_gt_i32 s2, 63
	v_readfirstlane_b32 s0, v189
	s_cbranch_scc1 .LBB0_724
	v_and_b32_e32 v155, 63, v189
	v_lshrrev_b32_e32 v156, 6, v189
	v_and_b32_e32 v156, 7, v156
	v_lshlrev_b32_e32 v156, 13, v156
	v_add_u32_e32 v156, 0x10000, v156
	v_lshrrev_b32_e32 v182, 2, v155
	v_and_b32_e32 v165, 31, v155
	v_sub_u32_e32 v182, v182, v165
	v_mul_i32_i24_e32 v182, 0x1600, v182
	v_and_b32_e32 v165, 3, v155
	v_lshrrev_b32_e32 v183, 5, v155
	v_sub_u32_e32 v165, v165, v183
	v_lshl_add_u32 v182, v165, 4, v182
	v_ashrrev_i32_e32 v183, 31, v182
	v_lshrrev_b32_e32 v194, 4, v155
	v_xor_b32_e32 v194, v194, v155
	v_and_b32_e32 v194, 3, v194
	v_lshlrev_b32_e32 v194, 4, v194
	v_lshrrev_b32_e32 v165, 2, v155
	v_lshl_add_u32 v194, v165, 6, v194
	v_add_u32_e32 v194, v156, v194
	v_and_b32_e32 v165, 31, v155
	v_lshl_add_u32 v156, v165, 6, v156
	v_lshrrev_b32_e32 v165, 2, v155
	v_and_b32_e32 v165, 3, v165
	v_lshrrev_b32_e32 v155, 5, v155
	v_add_u32_e32 v244, 0, v155
	v_xor_b32_e32 v244, v244, v165
	v_lshl_add_u32 v244, v244, 4, v156
	v_add_u32_e32 v245, 2, v155
	v_xor_b32_e32 v245, v245, v165
	v_lshl_add_u32 v245, v245, 4, v156
	s_mov_b32 s80, 0x16000
	s_mov_b32 s81, 0
	s_lshr_b32 s6, s0, 6
	s_mul_i32 s0, s6, 0x160
	s_mov_b32 s1, 0
	s_lshl_b64 s[0:1], s[0:1], 1
	s_add_u32 s4, s24, s0
	s_addc_u32 s5, s25, s1
	v_bfe_u32 v2, v189, 5, 1
	s_add_u32 s0, s33, s0
	v_lshlrev_b32_e32 v34, 4, v2
	v_mov_b32_e32 v35, 0
	s_addc_u32 s1, s56, s1
	v_and_b32_e32 v40, 31, v189
	v_lshl_add_u64 v[38:39], s[0:1], 0, v[34:35]
	s_lshl_b32 s0, s6, 13
	s_add_i32 s0, s0, 0
	v_lshlrev_b32_e32 v2, 10, v2
	s_waitcnt lgkmcnt(0)
	v_lshlrev_b32_e32 v3, 2, v40
	v_add3_u32 v41, s0, v2, v3
	v_and_b32_e32 v4, 28, v192
	s_movk_i32 s0, 0x80
	v_and_or_b32 v42, v191, s0, v4
	v_mbcnt_lo_u32_b32 v4, -1, 0
	v_mbcnt_hi_u32_b32 v4, -1, v4
	v_and_b32_e32 v6, 64, v4
	v_xor_b32_e32 v5, 1, v4
	v_add_u32_e32 v6, 64, v6
	v_cmp_lt_i32_e32 vcc, v5, v6
	v_and_b32_e32 v2, 0x3f00, v191
	v_add_u32_e32 v2, 0, v2
	v_cndmask_b32_e32 v5, v4, v5, vcc
	v_lshlrev_b32_e32 v43, 2, v5
	v_xor_b32_e32 v5, 2, v4
	v_cmp_lt_i32_e32 vcc, v5, v6
	v_and_b32_e32 v3, 0xf0, v191
	v_lshl_add_u64 v[36:37], s[4:5], 0, v[34:35]
	v_cndmask_b32_e32 v5, v4, v5, vcc
	v_lshlrev_b32_e32 v44, 2, v5
	v_xor_b32_e32 v5, 4, v4
	v_cmp_lt_i32_e32 vcc, v5, v6
	s_lshl_b32 s4, s2, 3
	s_lshl_b32 s5, s3, 3
	v_cndmask_b32_e32 v5, v4, v5, vcc
	v_lshlrev_b32_e32 v45, 2, v5
	v_xor_b32_e32 v5, 8, v4
	v_cmp_lt_i32_e32 vcc, v5, v6
	s_lshl_b32 s6, s2, 4
	s_lshl_b32 s7, s3, 4
	v_cndmask_b32_e32 v4, v4, v5, vcc
	v_lshlrev_b32_e32 v46, 2, v4
	v_cmp_eq_u32_e32 vcc, 0, v190
	s_lshl_b32 s12, s2, 5
	s_lshl_b32 s13, s3, 5
	s_movk_i32 s14, 0x1600
	s_mov_b32 s15, 0xb0000
	v_add_u32_e32 v47, v2, v3
	v_add_u32_e32 v48, 0x800, v41
	v_add_u32_e32 v49, 0x1000, v41
	v_add_u32_e32 v50, 0x1800, v41
	s_mov_b32 s16, s2
	s_branch .LBB0_722

; template <class EpiS>
; DI void sample_gemm(LAS unsigned char* lds, const bf16_t* A, const bf16_t* Bt, int nN, int K, const EpiS& E) {
;     ...
;     for (int un = (int)blockIdx.x; un < nunits; un += (int)gridDim.x) {
;         const int rb = un & 3, wc = (un >> 2) & 3, pn = un >> 4;
;         const bf16_t* ap = A + (size_t)(MP + rb * 32 + r32) * K + w * kw + h * 8;
;         const bf16_t* b0p = Bt + (size_t)(pn * 256 + wc * 32 + r32) * K + w * kw + h * 8;
;         const bf16_t* b1p = b0p + (size_t)128 * K;
;         f32x16 c0, c1;
; #pragma unroll
;         for (int r = 0; r < 16; ++r) { c0[r] = 0.f; c1[r] = 0.f; }
; #pragma unroll 8
;         for (int ks = 0; ks < nk; ++ks) {
;             const bf16x8 a = *(const bf16x8*)(ap + ks * 16), b0 = *(const bf16x8*)(b0p + ks * 16), b1 = *(const bf16x8*)(b1p + ks * 16);
;             c0 = __builtin_amdgcn_mfma_f32_32x32x16_bf16(a, b0, c0, 0, 0, 0);
;             c1 = __builtin_amdgcn_mfma_f32_32x32x16_bf16(a, b1, c1, 0, 0, 0);
;         }
.LBB0_722:
	s_and_b32 s17, s12, 0x60
	s_bitset1_b32 s17, 15
	v_or_b32_e32 v2, s17, v40
	v_mul_u32_u24_e32 v2, 0xb00, v2
	v_lshlrev_b32_e32 v34, 1, v2
	v_lshl_add_u64 v[76:77], v[36:37], 0, v[34:35]
	s_and_b32 s0, s6, 0xffffff00
	s_and_b32 s1, s4, 0x60
	s_or_b32 s18, s0, s1
	v_or_b32_e32 v2, s18, v40
	v_mad_i64_i32 v[78:79], s[0:1], v2, s14, v[38:39]
	s_waitcnt lgkmcnt(0)
	v_add_co_u32_e64 v80, s[0:1], s15, v78
	v_addc_co_u32_e64 v81, s[0:1], 0, v79, s[0:1]
	v_lshl_add_u64 v[240:241], v[76:77], 0, v[182:183]
	v_lshl_add_u64 v[242:243], v[240:241], 0, s[80:81]
	v_lshl_add_u64 v[248:249], v[78:79], 0, v[182:183]
	v_lshl_add_u64 v[250:251], v[248:249], 0, s[80:81]
	v_lshl_add_u64 v[252:253], v[80:81], 0, v[182:183]
	v_lshl_add_u64 v[254:255], v[252:253], 0, s[80:81]
	global_load_dwordx4 v[82:85], v[240:241], off
	global_load_dwordx4 v[86:89], v[242:243], off
	global_load_dwordx4 v[90:93], v[248:249], off
	global_load_dwordx4 v[94:97], v[250:251], off
	global_load_dwordx4 v[98:101], v[252:253], off
	global_load_dwordx4 v[102:105], v[254:255], off
	global_load_dwordx4 v[106:109], v[240:241], off offset:64
	global_load_dwordx4 v[110:113], v[242:243], off offset:64
	global_load_dwordx4 v[132:135], v[248:249], off offset:64
	global_load_dwordx4 v[136:139], v[250:251], off offset:64
	global_load_dwordx4 v[140:143], v[252:253], off offset:64
	global_load_dwordx4 v[144:147], v[254:255], off offset:64
	global_load_dwordx4 v[148:151], v[240:241], off offset:128
	global_load_dwordx4 v[166:169], v[242:243], off offset:128
	global_load_dwordx4 v[170:173], v[248:249], off offset:128
	global_load_dwordx4 v[174:177], v[250:251], off offset:128
	global_load_dwordx4 v[198:201], v[252:253], off offset:128
	global_load_dwordx4 v[202:205], v[254:255], off offset:128
	global_load_dwordx4 v[216:219], v[240:241], off offset:192
	global_load_dwordx4 v[220:223], v[242:243], off offset:192
	global_load_dwordx4 v[224:227], v[248:249], off offset:192
	global_load_dwordx4 v[228:231], v[250:251], off offset:192
	global_load_dwordx4 v[232:235], v[252:253], off offset:192
	global_load_dwordx4 v[236:239], v[254:255], off offset:192
	s_waitcnt vmcnt(18)
	ds_write_b128 v194, v[82:85]
	ds_write_b128 v194, v[86:89] offset:1024
	ds_write_b128 v194, v[90:93] offset:2048
	ds_write_b128 v194, v[94:97] offset:3072
	ds_write_b128 v194, v[98:101] offset:4096
	ds_write_b128 v194, v[102:105] offset:5120
	ds_read_b128 v[82:85], v244
	ds_read_b128 v[86:89], v245
	ds_read_b128 v[90:93], v244 offset:2048
	ds_read_b128 v[94:97], v245 offset:2048
	ds_read_b128 v[98:101], v244 offset:4096
	ds_read_b128 v[102:105], v245 offset:4096
	s_waitcnt lgkmcnt(0)
	v_mfma_f32_32x32x16_bf16 v[2:17], v[82:85], v[90:93], 0
	v_mfma_f32_32x32x16_bf16 v[2:17], v[86:89], v[94:97], v[2:17]
	v_mfma_f32_32x32x16_bf16 v[18:33], v[82:85], v[98:101], 0
	v_mfma_f32_32x32x16_bf16 v[18:33], v[86:89], v[102:105], v[18:33]
	global_load_dwordx4 v[82:85], v[240:241], off offset:256
	global_load_dwordx4 v[86:89], v[242:243], off offset:256
	global_load_dwordx4 v[90:93], v[248:249], off offset:256
	global_load_dwordx4 v[94:97], v[250:251], off offset:256
	global_load_dwordx4 v[98:101], v[252:253], off offset:256
	global_load_dwordx4 v[102:105], v[254:255], off offset:256
	s_waitcnt vmcnt(18)
	ds_write_b128 v194, v[106:109]
	ds_write_b128 v194, v[110:113] offset:1024
	ds_write_b128 v194, v[132:135] offset:2048
	ds_write_b128 v194, v[136:139] offset:3072
	ds_write_b128 v194, v[140:143] offset:4096
	ds_write_b128 v194, v[144:147] offset:5120
	ds_read_b128 v[106:109], v244
	ds_read_b128 v[110:113], v245
	ds_read_b128 v[132:135], v244 offset:2048
	ds_read_b128 v[136:139], v245 offset:2048
	ds_read_b128 v[140:143], v244 offset:4096
	ds_read_b128 v[144:147], v245 offset:4096
	s_waitcnt lgkmcnt(0)
	v_mfma_f32_32x32x16_bf16 v[2:17], v[106:109], v[132:135], v[2:17]
	v_mfma_f32_32x32x16_bf16 v[2:17], v[110:113], v[136:139], v[2:17]
	v_mfma_f32_32x32x16_bf16 v[18:33], v[106:109], v[140:143], v[18:33]
	v_mfma_f32_32x32x16_bf16 v[18:33], v[110:113], v[144:147], v[18:33]
	global_load_dwordx4 v[106:109], v[240:241], off offset:320
	global_load_dwordx4 v[110:113], v[242:243], off offset:320
	global_load_dwordx4 v[132:135], v[248:249], off offset:320
	global_load_dwordx4 v[136:139], v[250:251], off offset:320
	global_load_dwordx4 v[140:143], v[252:253], off offset:320
	global_load_dwordx4 v[144:147], v[254:255], off offset:320
	s_waitcnt vmcnt(18)
	ds_write_b128 v194, v[148:151]
	ds_write_b128 v194, v[166:169] offset:1024
	ds_write_b128 v194, v[170:173] offset:2048
	ds_write_b128 v194, v[174:177] offset:3072
	ds_write_b128 v194, v[198:201] offset:4096
	ds_write_b128 v194, v[202:205] offset:5120
	ds_read_b128 v[148:151], v244
	ds_read_b128 v[166:169], v245
	ds_read_b128 v[170:173], v244 offset:2048
	ds_read_b128 v[174:177], v245 offset:2048
	ds_read_b128 v[198:201], v244 offset:4096
	ds_read_b128 v[202:205], v245 offset:4096
	s_waitcnt lgkmcnt(0)
	v_mfma_f32_32x32x16_bf16 v[2:17], v[148:151], v[170:173], v[2:17]
	v_mfma_f32_32x32x16_bf16 v[2:17], v[166:169], v[174:177], v[2:17]
	v_mfma_f32_32x32x16_bf16 v[18:33], v[148:151], v[198:201], v[18:33]
	v_mfma_f32_32x32x16_bf16 v[18:33], v[166:169], v[202:205], v[18:33]
	global_load_dwordx4 v[148:151], v[240:241], off offset:384
	global_load_dwordx4 v[166:169], v[242:243], off offset:384
	global_load_dwordx4 v[170:173], v[248:249], off offset:384
	global_load_dwordx4 v[174:177], v[250:251], off offset:384
	global_load_dwordx4 v[198:201], v[252:253], off offset:384
	global_load_dwordx4 v[202:205], v[254:255], off offset:384
	s_waitcnt vmcnt(18)
; template <class EpiS>
; DI void sample_gemm(LAS unsigned char* lds, const bf16_t* A, const bf16_t* Bt, int nN, int K, const EpiS& E) {
;     ...
; #pragma unroll 8
;         for (int ks = 0; ks < nk; ++ks) {
;             const bf16x8 a = *(const bf16x8*)(ap + ks * 16), b0 = *(const bf16x8*)(b0p + ks * 16), b1 = *(const bf16x8*)(b1p + ks * 16);
;             c0 = __builtin_amdgcn_mfma_f32_32x32x16_bf16(a, b0, c0, 0, 0, 0);
;             c1 = __builtin_amdgcn_mfma_f32_32x32x16_bf16(a, b1, c1, 0, 0, 0);
;         }
	ds_write_b128 v194, v[216:219]
	ds_write_b128 v194, v[220:223] offset:1024
	ds_write_b128 v194, v[224:227] offset:2048
	ds_write_b128 v194, v[228:231] offset:3072
	ds_write_b128 v194, v[232:235] offset:4096
	ds_write_b128 v194, v[236:239] offset:5120
	ds_read_b128 v[216:219], v244
	ds_read_b128 v[220:223], v245
	ds_read_b128 v[224:227], v244 offset:2048
	ds_read_b128 v[228:231], v245 offset:2048
	ds_read_b128 v[232:235], v244 offset:4096
	ds_read_b128 v[236:239], v245 offset:4096
	s_waitcnt lgkmcnt(0)
	v_mfma_f32_32x32x16_bf16 v[2:17], v[216:219], v[224:227], v[2:17]
	v_mfma_f32_32x32x16_bf16 v[2:17], v[220:223], v[228:231], v[2:17]
	v_mfma_f32_32x32x16_bf16 v[18:33], v[216:219], v[232:235], v[18:33]
	v_mfma_f32_32x32x16_bf16 v[18:33], v[220:223], v[236:239], v[18:33]
	global_load_dwordx4 v[216:219], v[240:241], off offset:448
	global_load_dwordx4 v[220:223], v[242:243], off offset:448
	global_load_dwordx4 v[224:227], v[248:249], off offset:448
	global_load_dwordx4 v[228:231], v[250:251], off offset:448
	global_load_dwordx4 v[232:235], v[252:253], off offset:448
	global_load_dwordx4 v[236:239], v[254:255], off offset:448
	s_waitcnt vmcnt(18)
	ds_write_b128 v194, v[82:85]
	ds_write_b128 v194, v[86:89] offset:1024
	ds_write_b128 v194, v[90:93] offset:2048
	ds_write_b128 v194, v[94:97] offset:3072
	ds_write_b128 v194, v[98:101] offset:4096
	ds_write_b128 v194, v[102:105] offset:5120
	ds_read_b128 v[82:85], v244
	ds_read_b128 v[86:89], v245
	ds_read_b128 v[90:93], v244 offset:2048
	ds_read_b128 v[94:97], v245 offset:2048
	ds_read_b128 v[98:101], v244 offset:4096
	ds_read_b128 v[102:105], v245 offset:4096
	s_waitcnt lgkmcnt(0)
	v_mfma_f32_32x32x16_bf16 v[2:17], v[82:85], v[90:93], v[2:17]
	v_mfma_f32_32x32x16_bf16 v[2:17], v[86:89], v[94:97], v[2:17]
	v_mfma_f32_32x32x16_bf16 v[18:33], v[82:85], v[98:101], v[18:33]
	v_mfma_f32_32x32x16_bf16 v[18:33], v[86:89], v[102:105], v[18:33]
	global_load_dwordx4 v[82:85], v[240:241], off offset:512
	global_load_dwordx4 v[86:89], v[242:243], off offset:512
	global_load_dwordx4 v[90:93], v[248:249], off offset:512
	global_load_dwordx4 v[94:97], v[250:251], off offset:512
	global_load_dwordx4 v[98:101], v[252:253], off offset:512
	global_load_dwordx4 v[102:105], v[254:255], off offset:512
	s_waitcnt vmcnt(18)
	ds_write_b128 v194, v[106:109]
	ds_write_b128 v194, v[110:113] offset:1024
	ds_write_b128 v194, v[132:135] offset:2048
	ds_write_b128 v194, v[136:139] offset:3072
	ds_write_b128 v194, v[140:143] offset:4096
	ds_write_b128 v194, v[144:147] offset:5120
	ds_read_b128 v[106:109], v244
	ds_read_b128 v[110:113], v245
	ds_read_b128 v[132:135], v244 offset:2048
	ds_read_b128 v[136:139], v245 offset:2048
	ds_read_b128 v[140:143], v244 offset:4096
	ds_read_b128 v[144:147], v245 offset:4096
	s_waitcnt lgkmcnt(0)
	v_mfma_f32_32x32x16_bf16 v[2:17], v[106:109], v[132:135], v[2:17]
	v_mfma_f32_32x32x16_bf16 v[2:17], v[110:113], v[136:139], v[2:17]
	v_mfma_f32_32x32x16_bf16 v[18:33], v[106:109], v[140:143], v[18:33]
	v_mfma_f32_32x32x16_bf16 v[18:33], v[110:113], v[144:147], v[18:33]
	global_load_dwordx4 v[106:109], v[240:241], off offset:576
	global_load_dwordx4 v[110:113], v[242:243], off offset:576
	global_load_dwordx4 v[132:135], v[248:249], off offset:576
	global_load_dwordx4 v[136:139], v[250:251], off offset:576
	global_load_dwordx4 v[140:143], v[252:253], off offset:576
	global_load_dwordx4 v[144:147], v[254:255], off offset:576
	s_waitcnt vmcnt(18)
	ds_write_b128 v194, v[148:151]
	ds_write_b128 v194, v[166:169] offset:1024
	ds_write_b128 v194, v[170:173] offset:2048
	ds_write_b128 v194, v[174:177] offset:3072
	ds_write_b128 v194, v[198:201] offset:4096
	ds_write_b128 v194, v[202:205] offset:5120
	ds_read_b128 v[148:151], v244
	ds_read_b128 v[166:169], v245
	ds_read_b128 v[170:173], v244 offset:2048
	ds_read_b128 v[174:177], v245 offset:2048
	ds_read_b128 v[198:201], v244 offset:4096
	ds_read_b128 v[202:205], v245 offset:4096
	s_waitcnt lgkmcnt(0)
	v_mfma_f32_32x32x16_bf16 v[2:17], v[148:151], v[170:173], v[2:17]
	v_mfma_f32_32x32x16_bf16 v[2:17], v[166:169], v[174:177], v[2:17]
	v_mfma_f32_32x32x16_bf16 v[18:33], v[148:151], v[198:201], v[18:33]
	v_mfma_f32_32x32x16_bf16 v[18:33], v[166:169], v[202:205], v[18:33]
	global_load_dwordx4 v[148:151], v[240:241], off offset:640
	global_load_dwordx4 v[166:169], v[242:243], off offset:640
	global_load_dwordx4 v[170:173], v[248:249], off offset:640
	global_load_dwordx4 v[174:177], v[250:251], off offset:640
	global_load_dwordx4 v[198:201], v[252:253], off offset:640
	global_load_dwordx4 v[202:205], v[254:255], off offset:640
	s_waitcnt vmcnt(18)
	ds_write_b128 v194, v[216:219]
	ds_write_b128 v194, v[220:223] offset:1024
	ds_write_b128 v194, v[224:227] offset:2048
	ds_write_b128 v194, v[228:231] offset:3072
	ds_write_b128 v194, v[232:235] offset:4096
	ds_write_b128 v194, v[236:239] offset:5120
	ds_read_b128 v[216:219], v244
	ds_read_b128 v[220:223], v245
	ds_read_b128 v[224:227], v244 offset:2048
	ds_read_b128 v[228:231], v245 offset:2048
	ds_read_b128 v[232:235], v244 offset:4096
	ds_read_b128 v[236:239], v245 offset:4096
	s_waitcnt lgkmcnt(0)
	v_mfma_f32_32x32x16_bf16 v[2:17], v[216:219], v[224:227], v[2:17]
	v_mfma_f32_32x32x16_bf16 v[2:17], v[220:223], v[228:231], v[2:17]
	v_mfma_f32_32x32x16_bf16 v[18:33], v[216:219], v[232:235], v[18:33]
	v_mfma_f32_32x32x16_bf16 v[18:33], v[220:223], v[236:239], v[18:33]
	s_waitcnt vmcnt(12)
; #define LAS __attribute__((address_space(3)))
; DI float bflo(unsigned u) { return __uint_as_float(u << 16); }
; DI float bfhi(unsigned u) { return __uint_as_float(u & 0xffff0000u); }
; DI float red16(float v) { v += __shfl_xor(v, 1); v += __shfl_xor(v, 2); v += __shfl_xor(v, 4); v += __shfl_xor(v, 8); return v; }
; DI u32x2 pk4(const f32x4 a) { return (u32x2){pk2(a[0], a[1]), pk2(a[2], a[3])}; }
;     DI void operator()(const f32x4 v, int row, int pn, int wc, int bj, int cl) const {
;         const int col = pn * 256 + bj * 128 + wc * 32 + cl;
;         f32x4 x;
;         if (MODE == 0) x = *(const f32x4*)(xin + (size_t)row * D + col);
;         else { const u32x2 w = *(const u32x2*)(XN + (size_t)row * D + col); x = (f32x4){bflo(w.x), bfhi(w.x), bflo(w.y), bfhi(w.y)}; }
;         x += v;
;         if (MODE == 2) *(f32x4*)(out + (size_t)row * D + col) = x;
;         else {
;             *(u32x2*)(XN + (size_t)row * D + col) = pk4(x);
;             const float ssq = red16((x[0] * x[0] + x[1] * x[1]) + (x[2] * x[2] + x[3] * x[3]));
;             if ((threadIdx.x & 15) == 0) atomicAdd(SS + row, ssq);
;         }
; template <class EpiS>
; DI void sample_gemm(LAS unsigned char* lds, const bf16_t* A, const bf16_t* Bt, int nN, int K, const EpiS& E) {
;     ...
; #pragma unroll 8
;         for (int ks = 0; ks < nk; ++ks) {
;             const bf16x8 a = *(const bf16x8*)(ap + ks * 16), b0 = *(const bf16x8*)(b0p + ks * 16), b1 = *(const bf16x8*)(b1p + ks * 16);
;             c0 = __builtin_amdgcn_mfma_f32_32x32x16_bf16(a, b0, c0, 0, 0, 0);
;             c1 = __builtin_amdgcn_mfma_f32_32x32x16_bf16(a, b1, c1, 0, 0, 0);
;         }
;         __syncthreads();
;         LAS float* part = (LAS float*)(lds + w * 8192);
; #pragma unroll
;         for (int r = 0; r < 16; ++r) { const int row = (r & 3) + 8 * (r >> 2) + 4 * h; part[row * 64 + r32] = c0[r]; part[row * 64 + 32 + r32] = c1[r]; }
;         __syncthreads();
;         f32x4 v = (f32x4){0.f, 0.f, 0.f, 0.f};
; #pragma unroll
;         for (int ww = 0; ww < 8; ++ww) v += *(const LAS f32x4*)(lds + ww * 8192 + (tid >> 4) * 256 + (tid & 15) * 16);
;         E(v, MP + rb * 32 + (tid >> 4), pn, wc, (tid >> 3) & 1, 4 * (tid & 7));
	ds_write_b128 v194, v[82:85]
	ds_write_b128 v194, v[86:89] offset:1024
	ds_write_b128 v194, v[90:93] offset:2048
	ds_write_b128 v194, v[94:97] offset:3072
	ds_write_b128 v194, v[98:101] offset:4096
	ds_write_b128 v194, v[102:105] offset:5120
	ds_read_b128 v[82:85], v244
	ds_read_b128 v[86:89], v245
	ds_read_b128 v[90:93], v244 offset:2048
	ds_read_b128 v[94:97], v245 offset:2048
	ds_read_b128 v[98:101], v244 offset:4096
	ds_read_b128 v[102:105], v245 offset:4096
	s_waitcnt lgkmcnt(0)
	v_mfma_f32_32x32x16_bf16 v[2:17], v[82:85], v[90:93], v[2:17]
	v_mfma_f32_32x32x16_bf16 v[2:17], v[86:89], v[94:97], v[2:17]
	v_mfma_f32_32x32x16_bf16 v[18:33], v[82:85], v[98:101], v[18:33]
	v_mfma_f32_32x32x16_bf16 v[18:33], v[86:89], v[102:105], v[18:33]
	s_waitcnt vmcnt(6)
	ds_write_b128 v194, v[106:109]
	ds_write_b128 v194, v[110:113] offset:1024
	ds_write_b128 v194, v[132:135] offset:2048
	ds_write_b128 v194, v[136:139] offset:3072
	ds_write_b128 v194, v[140:143] offset:4096
	ds_write_b128 v194, v[144:147] offset:5120
	ds_read_b128 v[106:109], v244
	ds_read_b128 v[110:113], v245
	ds_read_b128 v[132:135], v244 offset:2048
	ds_read_b128 v[136:139], v245 offset:2048
	ds_read_b128 v[140:143], v244 offset:4096
	ds_read_b128 v[144:147], v245 offset:4096
	s_waitcnt lgkmcnt(0)
	v_mfma_f32_32x32x16_bf16 v[2:17], v[106:109], v[132:135], v[2:17]
	v_mfma_f32_32x32x16_bf16 v[2:17], v[110:113], v[136:139], v[2:17]
	v_mfma_f32_32x32x16_bf16 v[18:33], v[106:109], v[140:143], v[18:33]
	v_mfma_f32_32x32x16_bf16 v[18:33], v[110:113], v[144:147], v[18:33]
	s_waitcnt vmcnt(0)
	ds_write_b128 v194, v[148:151]
	ds_write_b128 v194, v[166:169] offset:1024
	ds_write_b128 v194, v[170:173] offset:2048
	ds_write_b128 v194, v[174:177] offset:3072
	ds_write_b128 v194, v[198:201] offset:4096
	ds_write_b128 v194, v[202:205] offset:5120
	ds_read_b128 v[148:151], v244
	ds_read_b128 v[166:169], v245
	ds_read_b128 v[170:173], v244 offset:2048
	ds_read_b128 v[174:177], v245 offset:2048
	ds_read_b128 v[198:201], v244 offset:4096
	ds_read_b128 v[202:205], v245 offset:4096
	s_waitcnt lgkmcnt(0)
	v_mfma_f32_32x32x16_bf16 v[2:17], v[148:151], v[170:173], v[2:17]
	v_mfma_f32_32x32x16_bf16 v[2:17], v[166:169], v[174:177], v[2:17]
	v_mfma_f32_32x32x16_bf16 v[18:33], v[148:151], v[198:201], v[18:33]
	v_mfma_f32_32x32x16_bf16 v[18:33], v[166:169], v[202:205], v[18:33]
	s_barrier
	s_nop 11
	ds_write2_b32 v41, v2, v18 offset1:32
	ds_write2_b32 v41, v3, v19 offset0:64 offset1:96
	ds_write2_b32 v41, v4, v20 offset0:128 offset1:160
	ds_write2_b32 v41, v5, v21 offset0:192 offset1:224
	ds_write2_b32 v48, v6, v22 offset1:32
	ds_write2_b32 v48, v7, v23 offset0:64 offset1:96
	ds_write2_b32 v48, v8, v24 offset0:128 offset1:160
	ds_write2_b32 v48, v9, v25 offset0:192 offset1:224
	ds_write2_b32 v49, v10, v26 offset1:32
	ds_write2_b32 v49, v11, v27 offset0:64 offset1:96
	ds_write2_b32 v49, v12, v28 offset0:128 offset1:160
	ds_write2_b32 v49, v13, v29 offset0:192 offset1:224
	ds_write2_b32 v50, v14, v30 offset1:32
	ds_write2_b32 v50, v15, v31 offset0:64 offset1:96
	ds_write2_b32 v50, v16, v32 offset0:128 offset1:160
	ds_write2_b32 v50, v17, v33 offset0:192 offset1:224
	v_add_u32_e32 v2, s17, v188
	v_or_b32_e32 v4, s18, v42
	v_lshlrev_b32_e32 v34, 11, v2
	v_lshl_add_u64 v[6:7], s[34:35], 0, v[34:35]
	v_ashrrev_i32_e32 v5, 31, v4
	v_lshl_add_u64 v[18:19], v[4:5], 1, v[6:7]
	s_waitcnt lgkmcnt(0)
	s_barrier
	global_load_dwordx2 v[20:21], v[18:19], off
	ds_read_b128 v[4:7], v47
	ds_read_b128 v[8:11], v47 offset:8192
	ds_read_b128 v[12:15], v47 offset:16384
	s_waitcnt lgkmcnt(2)
	v_pk_add_f32 v[6:7], v[6:7], 0 op_sel_hi:[1,0]
	v_pk_add_f32 v[16:17], v[4:5], 0 op_sel_hi:[1,0]
	s_waitcnt lgkmcnt(1)
	v_pk_add_f32 v[10:11], v[6:7], v[10:11]
	ds_read_b128 v[4:7], v47 offset:24576
	v_pk_add_f32 v[16:17], v[16:17], v[8:9]
	s_waitcnt lgkmcnt(1)
	v_pk_add_f32 v[14:15], v[10:11], v[14:15]
	ds_read_b128 v[8:11], v47 offset:32768
	v_pk_add_f32 v[12:13], v[16:17], v[12:13]
	s_waitcnt lgkmcnt(1)
	v_pk_add_f32 v[14:15], v[14:15], v[6:7]
	v_pk_add_f32 v[16:17], v[12:13], v[4:5]
	ds_read_b128 v[4:7], v47 offset:40960
	s_waitcnt lgkmcnt(1)
	v_pk_add_f32 v[22:23], v[14:15], v[10:11]
	ds_read_b128 v[10:13], v47 offset:49152
	v_pk_add_f32 v[8:9], v[16:17], v[8:9]
	ds_read_b128 v[14:17], v47 offset:57344
	s_waitcnt lgkmcnt(2)
	v_pk_add_f32 v[6:7], v[22:23], v[6:7]
	v_pk_add_f32 v[4:5], v[8:9], v[4:5]
	s_waitcnt lgkmcnt(1)
	v_pk_add_f32 v[6:7], v[6:7], v[12:13]
	v_pk_add_f32 v[4:5], v[4:5], v[10:11]
	s_waitcnt lgkmcnt(0)
	v_pk_add_f32 v[6:7], v[6:7], v[16:17]
	v_pk_add_f32 v[4:5], v[4:5], v[14:15]
	s_waitcnt vmcnt(0)
	v_lshlrev_b32_e32 v8, 16, v20
	v_and_b32_e32 v9, 0xffff0000, v20
	v_lshlrev_b32_e32 v10, 16, v21
	v_and_b32_e32 v11, 0xffff0000, v21
	v_pk_add_f32 v[6:7], v[6:7], v[10:11]
	v_pk_add_f32 v[8:9], v[4:5], v[8:9]
	v_mul_f32_e32 v4, v7, v7
	v_mul_f32_e32 v3, v9, v9
	v_fmac_f32_e32 v3, v8, v8
	v_fmac_f32_e32 v4, v6, v6
	v_add_f32_e32 v3, v3, v4
	ds_bpermute_b32 v4, v43, v3
	v_cvt_pk_bf16_f32 v8, v8, v9
	v_cvt_pk_bf16_f32 v9, v6, v7
	global_store_dwordx2 v[18:19], v[8:9], off
	s_waitcnt lgkmcnt(0)
	v_add_f32_e32 v3, v3, v4
	ds_bpermute_b32 v4, v44, v3
	s_waitcnt lgkmcnt(0)
	v_add_f32_e32 v3, v3, v4
	ds_bpermute_b32 v4, v45, v3
	s_waitcnt lgkmcnt(0)
	v_add_f32_e32 v3, v3, v4
	ds_bpermute_b32 v4, v46, v3
	s_and_saveexec_b64 s[0:1], vcc
	s_cbranch_execz .LBB0_721
	s_waitcnt lgkmcnt(0)
	v_add_f32_e32 v3, v3, v4
	v_lshlrev_b32_e32 v2, 2, v2
	global_atomic_add_f32 v2, v3, s[10:11]
	s_branch .LBB0_721

; template <class EpiS>
; DI void sample_gemm(LAS unsigned char* lds, const bf16_t* A, const bf16_t* Bt, int nN, int K, const EpiS& E) {
;     const int tid = threadIdx.x, lane = tid & 63, w = __builtin_amdgcn_readfirstlane(tid >> 6), r32 = lane & 31, h = lane >> 5;
;     const int nunits = 16 * nN, kw = K >> 3, nk = kw >> 4;
;     for (int un = (int)blockIdx.x; un < nunits; un += (int)gridDim.x) {
;         const int rb = un & 3, wc = (un >> 2) & 3, pn = un >> 4;
;         const bf16_t* ap = A + (size_t)(MP + rb * 32 + r32) * K + w * kw + h * 8;
;         const bf16_t* b0p = Bt + (size_t)(pn * 256 + wc * 32 + r32) * K + w * kw + h * 8;
;         const bf16_t* b1p = b0p + (size_t)128 * K;
;         f32x16 c0, c1;
; #pragma unroll
;         for (int r = 0; r < 16; ++r) { c0[r] = 0.f; c1[r] = 0.f; }
; #pragma unroll 8
;         for (int ks = 0; ks < nk; ++ks) {
;             const bf16x8 a = *(const bf16x8*)(ap + ks * 16), b0 = *(const bf16x8*)(b0p + ks * 16), b1 = *(const bf16x8*)(b1p + ks * 16);
;             c0 = __builtin_amdgcn_mfma_f32_32x32x16_bf16(a, b0, c0, 0, 0, 0);
;             c1 = __builtin_amdgcn_mfma_f32_32x32x16_bf16(a, b1, c1, 0, 0, 0);
;         }
.LBB0_1520:
	s_cmp_gt_i32 s2, 63
	v_readfirstlane_b32 s0, v153
	s_cbranch_scc1 .LBB0_1523
	v_and_b32_e32 v155, 63, v153
	v_lshrrev_b32_e32 v156, 6, v153
	v_and_b32_e32 v156, 7, v156
	v_lshlrev_b32_e32 v156, 13, v156
	v_add_u32_e32 v156, 0x10000, v156
	v_lshrrev_b32_e32 v182, 2, v155
	v_and_b32_e32 v165, 31, v155
	v_sub_u32_e32 v182, v182, v165
	v_mul_i32_i24_e32 v182, 0x1600, v182
	v_and_b32_e32 v165, 3, v155
	v_lshrrev_b32_e32 v183, 5, v155
	v_sub_u32_e32 v165, v165, v183
	v_lshl_add_u32 v182, v165, 4, v182
	v_ashrrev_i32_e32 v183, 31, v182
	v_lshrrev_b32_e32 v194, 4, v155
	v_xor_b32_e32 v194, v194, v155
	v_and_b32_e32 v194, 3, v194
	v_lshlrev_b32_e32 v194, 4, v194
	v_lshrrev_b32_e32 v165, 2, v155
	v_lshl_add_u32 v194, v165, 6, v194
	v_add_u32_e32 v194, v156, v194
	v_and_b32_e32 v165, 31, v155
	v_lshl_add_u32 v156, v165, 6, v156
	v_lshrrev_b32_e32 v165, 2, v155
	v_and_b32_e32 v165, 3, v165
	v_lshrrev_b32_e32 v155, 5, v155
	v_add_u32_e32 v244, 0, v155
	v_xor_b32_e32 v244, v244, v165
	v_lshl_add_u32 v244, v244, 4, v156
	v_add_u32_e32 v245, 2, v155
	v_xor_b32_e32 v245, v245, v165
	v_lshl_add_u32 v245, v245, 4, v156
	s_mov_b32 s80, 0x16000
	s_mov_b32 s81, 0
	s_lshr_b32 s6, s0, 6
	s_mul_i32 s0, s6, 0x160
	s_mov_b32 s1, 0
	s_lshl_b64 s[0:1], s[0:1], 1
	s_add_u32 s4, s24, s0
	s_addc_u32 s5, s25, s1
	v_bfe_u32 v0, v153, 5, 1
	s_add_u32 s0, s20, s0
	v_lshlrev_b32_e32 v32, 4, v0
	v_mov_b32_e32 v33, 0
	s_addc_u32 s1, s21, s1
	v_and_b32_e32 v38, 31, v153
	v_lshl_add_u64 v[36:37], s[0:1], 0, v[32:33]
	s_lshl_b32 s0, s6, 13
	s_add_i32 s0, s0, 0
	v_lshlrev_b32_e32 v0, 10, v0
	v_lshlrev_b32_e32 v1, 2, v38
	v_add3_u32 v39, s0, v0, v1
	v_and_b32_e32 v0, 0x3f00, v152
	v_add_u32_e32 v0, 0, v0
	v_and_b32_e32 v1, 0xf0, v152
	v_and_b32_e32 v2, 28, v154
	s_movk_i32 s0, 0x80
	v_lshl_add_u64 v[34:35], s[4:5], 0, v[32:33]
	v_lshrrev_b32_e32 v40, 4, v153
	v_and_or_b32 v41, v152, s0, v2
	s_lshl_b32 s0, s2, 3
	s_lshl_b32 s1, s3, 3
	s_lshl_b32 s4, s2, 4
	s_lshl_b32 s5, s3, 4
	s_lshl_b32 s6, s2, 5
	s_lshl_b32 s7, s3, 5
	s_movk_i32 s8, 0x1600
	s_mov_b32 s9, 0xb0000
	v_add_u32_e32 v42, v0, v1
	v_add_u32_e32 v43, 0x800, v39
	v_add_u32_e32 v44, 0x1000, v39
	v_add_u32_e32 v45, 0x1800, v39
.LBB0_1522:
	s_and_b32 s11, s4, 0xffffff00
	s_and_b32 s12, s0, 0x60
	s_and_b32 s10, s6, 0x60
	s_or_b32 s11, s11, s12
	s_bitset1_b32 s10, 15
	v_or_b32_e32 v1, s11, v38
	v_or_b32_e32 v0, s10, v38
	v_mad_i64_i32 v[70:71], s[12:13], v1, s8, v[36:37]
	v_mul_u32_u24_e32 v0, 0xb00, v0
	v_add_co_u32_e32 v72, vcc, s9, v70
	v_lshlrev_b32_e32 v32, 1, v0
	s_nop 0
	v_addc_co_u32_e32 v73, vcc, 0, v71, vcc
	v_lshl_add_u64 v[74:75], v[34:35], 0, v[32:33]
	s_add_i32 s2, s2, s3
	s_add_i32 s0, s0, s1
	s_add_i32 s4, s4, s5
	s_add_i32 s6, s6, s7
	s_cmp_lt_i32 s2, 64
	v_add_u32_e32 v60, s10, v40
	v_or_b32_e32 v58, s11, v41
	v_lshlrev_b32_e32 v32, 11, v60
	v_ashrrev_i32_e32 v59, 31, v58
	v_lshl_add_u64 v[50:51], s[34:35], 0, v[32:33]
	v_lshl_add_u64 v[50:51], v[58:59], 1, v[50:51]
	v_lshlrev_b32_e32 v32, 12, v60
	v_lshl_add_u64 v[240:241], v[74:75], 0, v[182:183]
	v_lshl_add_u64 v[242:243], v[240:241], 0, s[80:81]
	v_lshl_add_u64 v[248:249], v[70:71], 0, v[182:183]
	v_lshl_add_u64 v[250:251], v[248:249], 0, s[80:81]
	v_lshl_add_u64 v[252:253], v[72:73], 0, v[182:183]
	v_lshl_add_u64 v[254:255], v[252:253], 0, s[80:81]
	global_load_dwordx4 v[82:85], v[240:241], off
	global_load_dwordx4 v[86:89], v[242:243], off
	global_load_dwordx4 v[90:93], v[248:249], off
	global_load_dwordx4 v[94:97], v[250:251], off
	global_load_dwordx4 v[98:101], v[252:253], off
	global_load_dwordx4 v[102:105], v[254:255], off
	global_load_dwordx4 v[106:109], v[240:241], off offset:64
	global_load_dwordx4 v[110:113], v[242:243], off offset:64
	global_load_dwordx4 v[132:135], v[248:249], off offset:64
	global_load_dwordx4 v[136:139], v[250:251], off offset:64
	global_load_dwordx4 v[140:143], v[252:253], off offset:64
	global_load_dwordx4 v[144:147], v[254:255], off offset:64
	global_load_dwordx4 v[148:151], v[240:241], off offset:128
	global_load_dwordx4 v[166:169], v[242:243], off offset:128
	global_load_dwordx4 v[170:173], v[248:249], off offset:128
	global_load_dwordx4 v[174:177], v[250:251], off offset:128
	global_load_dwordx4 v[198:201], v[252:253], off offset:128
	global_load_dwordx4 v[202:205], v[254:255], off offset:128
	global_load_dwordx4 v[216:219], v[240:241], off offset:192
	global_load_dwordx4 v[220:223], v[242:243], off offset:192
	global_load_dwordx4 v[224:227], v[248:249], off offset:192
	global_load_dwordx4 v[228:231], v[250:251], off offset:192
	global_load_dwordx4 v[232:235], v[252:253], off offset:192
	global_load_dwordx4 v[236:239], v[254:255], off offset:192
	s_waitcnt vmcnt(18)
	ds_write_b128 v194, v[82:85]
	ds_write_b128 v194, v[86:89] offset:1024
	ds_write_b128 v194, v[90:93] offset:2048
	ds_write_b128 v194, v[94:97] offset:3072
	ds_write_b128 v194, v[98:101] offset:4096
	ds_write_b128 v194, v[102:105] offset:5120
	ds_read_b128 v[82:85], v244
	ds_read_b128 v[86:89], v245
	ds_read_b128 v[90:93], v244 offset:2048
	ds_read_b128 v[94:97], v245 offset:2048
	ds_read_b128 v[98:101], v244 offset:4096
	ds_read_b128 v[102:105], v245 offset:4096
	s_waitcnt lgkmcnt(0)
	v_mfma_f32_32x32x16_bf16 v[0:15], v[82:85], v[90:93], 0
	v_mfma_f32_32x32x16_bf16 v[0:15], v[86:89], v[94:97], v[0:15]
	v_mfma_f32_32x32x16_bf16 v[16:31], v[82:85], v[98:101], 0
	v_mfma_f32_32x32x16_bf16 v[16:31], v[86:89], v[102:105], v[16:31]
	global_load_dwordx4 v[82:85], v[240:241], off offset:256
	global_load_dwordx4 v[86:89], v[242:243], off offset:256
	global_load_dwordx4 v[90:93], v[248:249], off offset:256
	global_load_dwordx4 v[94:97], v[250:251], off offset:256
	global_load_dwordx4 v[98:101], v[252:253], off offset:256
	global_load_dwordx4 v[102:105], v[254:255], off offset:256
	s_waitcnt vmcnt(18)
; template <class EpiS>
; DI void sample_gemm(LAS unsigned char* lds, const bf16_t* A, const bf16_t* Bt, int nN, int K, const EpiS& E) {
;     ...
; #pragma unroll 8
;         for (int ks = 0; ks < nk; ++ks) {
;             const bf16x8 a = *(const bf16x8*)(ap + ks * 16), b0 = *(const bf16x8*)(b0p + ks * 16), b1 = *(const bf16x8*)(b1p + ks * 16);
;             c0 = __builtin_amdgcn_mfma_f32_32x32x16_bf16(a, b0, c0, 0, 0, 0);
;             c1 = __builtin_amdgcn_mfma_f32_32x32x16_bf16(a, b1, c1, 0, 0, 0);
;         }
	ds_write_b128 v194, v[106:109]
	ds_write_b128 v194, v[110:113] offset:1024
	ds_write_b128 v194, v[132:135] offset:2048
	ds_write_b128 v194, v[136:139] offset:3072
	ds_write_b128 v194, v[140:143] offset:4096
	ds_write_b128 v194, v[144:147] offset:5120
	ds_read_b128 v[106:109], v244
	ds_read_b128 v[110:113], v245
	ds_read_b128 v[132:135], v244 offset:2048
	ds_read_b128 v[136:139], v245 offset:2048
	ds_read_b128 v[140:143], v244 offset:4096
	ds_read_b128 v[144:147], v245 offset:4096
	s_waitcnt lgkmcnt(0)
	v_mfma_f32_32x32x16_bf16 v[0:15], v[106:109], v[132:135], v[0:15]
	v_mfma_f32_32x32x16_bf16 v[0:15], v[110:113], v[136:139], v[0:15]
	v_mfma_f32_32x32x16_bf16 v[16:31], v[106:109], v[140:143], v[16:31]
	v_mfma_f32_32x32x16_bf16 v[16:31], v[110:113], v[144:147], v[16:31]
	global_load_dwordx4 v[106:109], v[240:241], off offset:320
	global_load_dwordx4 v[110:113], v[242:243], off offset:320
	global_load_dwordx4 v[132:135], v[248:249], off offset:320
	global_load_dwordx4 v[136:139], v[250:251], off offset:320
	global_load_dwordx4 v[140:143], v[252:253], off offset:320
	global_load_dwordx4 v[144:147], v[254:255], off offset:320
	s_waitcnt vmcnt(18)
	ds_write_b128 v194, v[148:151]
	ds_write_b128 v194, v[166:169] offset:1024
	ds_write_b128 v194, v[170:173] offset:2048
	ds_write_b128 v194, v[174:177] offset:3072
	ds_write_b128 v194, v[198:201] offset:4096
	ds_write_b128 v194, v[202:205] offset:5120
	ds_read_b128 v[148:151], v244
	ds_read_b128 v[166:169], v245
	ds_read_b128 v[170:173], v244 offset:2048
	ds_read_b128 v[174:177], v245 offset:2048
	ds_read_b128 v[198:201], v244 offset:4096
	ds_read_b128 v[202:205], v245 offset:4096
	s_waitcnt lgkmcnt(0)
	v_mfma_f32_32x32x16_bf16 v[0:15], v[148:151], v[170:173], v[0:15]
	v_mfma_f32_32x32x16_bf16 v[0:15], v[166:169], v[174:177], v[0:15]
	v_mfma_f32_32x32x16_bf16 v[16:31], v[148:151], v[198:201], v[16:31]
	v_mfma_f32_32x32x16_bf16 v[16:31], v[166:169], v[202:205], v[16:31]
	global_load_dwordx4 v[148:151], v[240:241], off offset:384
	global_load_dwordx4 v[166:169], v[242:243], off offset:384
	global_load_dwordx4 v[170:173], v[248:249], off offset:384
	global_load_dwordx4 v[174:177], v[250:251], off offset:384
	global_load_dwordx4 v[198:201], v[252:253], off offset:384
	global_load_dwordx4 v[202:205], v[254:255], off offset:384
	s_waitcnt vmcnt(18)
	ds_write_b128 v194, v[216:219]
	ds_write_b128 v194, v[220:223] offset:1024
	ds_write_b128 v194, v[224:227] offset:2048
	ds_write_b128 v194, v[228:231] offset:3072
	ds_write_b128 v194, v[232:235] offset:4096
	ds_write_b128 v194, v[236:239] offset:5120
	ds_read_b128 v[216:219], v244
	ds_read_b128 v[220:223], v245
	ds_read_b128 v[224:227], v244 offset:2048
	ds_read_b128 v[228:231], v245 offset:2048
	ds_read_b128 v[232:235], v244 offset:4096
	ds_read_b128 v[236:239], v245 offset:4096
	s_waitcnt lgkmcnt(0)
	v_mfma_f32_32x32x16_bf16 v[0:15], v[216:219], v[224:227], v[0:15]
	v_mfma_f32_32x32x16_bf16 v[0:15], v[220:223], v[228:231], v[0:15]
	v_mfma_f32_32x32x16_bf16 v[16:31], v[216:219], v[232:235], v[16:31]
	v_mfma_f32_32x32x16_bf16 v[16:31], v[220:223], v[236:239], v[16:31]
	global_load_dwordx4 v[216:219], v[240:241], off offset:448
	global_load_dwordx4 v[220:223], v[242:243], off offset:448
	global_load_dwordx4 v[224:227], v[248:249], off offset:448
	global_load_dwordx4 v[228:231], v[250:251], off offset:448
	global_load_dwordx4 v[232:235], v[252:253], off offset:448
	global_load_dwordx4 v[236:239], v[254:255], off offset:448
	s_waitcnt vmcnt(18)
	ds_write_b128 v194, v[82:85]
	ds_write_b128 v194, v[86:89] offset:1024
	ds_write_b128 v194, v[90:93] offset:2048
	ds_write_b128 v194, v[94:97] offset:3072
	ds_write_b128 v194, v[98:101] offset:4096
	ds_write_b128 v194, v[102:105] offset:5120
	ds_read_b128 v[82:85], v244
	ds_read_b128 v[86:89], v245
	ds_read_b128 v[90:93], v244 offset:2048
	ds_read_b128 v[94:97], v245 offset:2048
	ds_read_b128 v[98:101], v244 offset:4096
	ds_read_b128 v[102:105], v245 offset:4096
	s_waitcnt lgkmcnt(0)
	v_mfma_f32_32x32x16_bf16 v[0:15], v[82:85], v[90:93], v[0:15]
	v_mfma_f32_32x32x16_bf16 v[0:15], v[86:89], v[94:97], v[0:15]
	v_mfma_f32_32x32x16_bf16 v[16:31], v[82:85], v[98:101], v[16:31]
	v_mfma_f32_32x32x16_bf16 v[16:31], v[86:89], v[102:105], v[16:31]
	global_load_dwordx4 v[82:85], v[240:241], off offset:512
	global_load_dwordx4 v[86:89], v[242:243], off offset:512
	global_load_dwordx4 v[90:93], v[248:249], off offset:512
	global_load_dwordx4 v[94:97], v[250:251], off offset:512
	global_load_dwordx4 v[98:101], v[252:253], off offset:512
	global_load_dwordx4 v[102:105], v[254:255], off offset:512
	s_waitcnt vmcnt(18)
	ds_write_b128 v194, v[106:109]
	ds_write_b128 v194, v[110:113] offset:1024
	ds_write_b128 v194, v[132:135] offset:2048
	ds_write_b128 v194, v[136:139] offset:3072
	ds_write_b128 v194, v[140:143] offset:4096
	ds_write_b128 v194, v[144:147] offset:5120
	ds_read_b128 v[106:109], v244
	ds_read_b128 v[110:113], v245
	ds_read_b128 v[132:135], v244 offset:2048
	ds_read_b128 v[136:139], v245 offset:2048
	ds_read_b128 v[140:143], v244 offset:4096
	ds_read_b128 v[144:147], v245 offset:4096
	s_waitcnt lgkmcnt(0)
	v_mfma_f32_32x32x16_bf16 v[0:15], v[106:109], v[132:135], v[0:15]
	v_mfma_f32_32x32x16_bf16 v[0:15], v[110:113], v[136:139], v[0:15]
	v_mfma_f32_32x32x16_bf16 v[16:31], v[106:109], v[140:143], v[16:31]
	v_mfma_f32_32x32x16_bf16 v[16:31], v[110:113], v[144:147], v[16:31]
	global_load_dwordx4 v[106:109], v[240:241], off offset:576
	global_load_dwordx4 v[110:113], v[242:243], off offset:576
	global_load_dwordx4 v[132:135], v[248:249], off offset:576
	global_load_dwordx4 v[136:139], v[250:251], off offset:576
	global_load_dwordx4 v[140:143], v[252:253], off offset:576
	global_load_dwordx4 v[144:147], v[254:255], off offset:576
	s_waitcnt vmcnt(18)
; #define LAS __attribute__((address_space(3)))
; DI float bflo(unsigned u) { return __uint_as_float(u << 16); }
; DI float bfhi(unsigned u) { return __uint_as_float(u & 0xffff0000u); }
;     DI void operator()(const f32x4 v, int row, int pn, int wc, int bj, int cl) const {
;         const int col = pn * 256 + bj * 128 + wc * 32 + cl;
;         f32x4 x;
;         if (MODE == 0) x = *(const f32x4*)(xin + (size_t)row * D + col);
;         else { const u32x2 w = *(const u32x2*)(XN + (size_t)row * D + col); x = (f32x4){bflo(w.x), bfhi(w.x), bflo(w.y), bfhi(w.y)}; }
;         x += v;
;         if (MODE == 2) *(f32x4*)(out + (size_t)row * D + col) = x;
; template <class EpiS>
; DI void sample_gemm(LAS unsigned char* lds, const bf16_t* A, const bf16_t* Bt, int nN, int K, const EpiS& E) {
;     ...
; #pragma unroll 8
;         for (int ks = 0; ks < nk; ++ks) {
;             const bf16x8 a = *(const bf16x8*)(ap + ks * 16), b0 = *(const bf16x8*)(b0p + ks * 16), b1 = *(const bf16x8*)(b1p + ks * 16);
;             c0 = __builtin_amdgcn_mfma_f32_32x32x16_bf16(a, b0, c0, 0, 0, 0);
;             c1 = __builtin_amdgcn_mfma_f32_32x32x16_bf16(a, b1, c1, 0, 0, 0);
;         }
;         __syncthreads();
;         LAS float* part = (LAS float*)(lds + w * 8192);
; #pragma unroll
;         for (int r = 0; r < 16; ++r) { const int row = (r & 3) + 8 * (r >> 2) + 4 * h; part[row * 64 + r32] = c0[r]; part[row * 64 + 32 + r32] = c1[r]; }
;         __syncthreads();
;         f32x4 v = (f32x4){0.f, 0.f, 0.f, 0.f};
; #pragma unroll
;         for (int ww = 0; ww < 8; ++ww) v += *(const LAS f32x4*)(lds + ww * 8192 + (tid >> 4) * 256 + (tid & 15) * 16);
;         E(v, MP + rb * 32 + (tid >> 4), pn, wc, (tid >> 3) & 1, 4 * (tid & 7));
	ds_write_b128 v194, v[148:151]
	ds_write_b128 v194, v[166:169] offset:1024
	ds_write_b128 v194, v[170:173] offset:2048
	ds_write_b128 v194, v[174:177] offset:3072
	ds_write_b128 v194, v[198:201] offset:4096
	ds_write_b128 v194, v[202:205] offset:5120
	ds_read_b128 v[148:151], v244
	ds_read_b128 v[166:169], v245
	ds_read_b128 v[170:173], v244 offset:2048
	ds_read_b128 v[174:177], v245 offset:2048
	ds_read_b128 v[198:201], v244 offset:4096
	ds_read_b128 v[202:205], v245 offset:4096
	s_waitcnt lgkmcnt(0)
	v_mfma_f32_32x32x16_bf16 v[0:15], v[148:151], v[170:173], v[0:15]
	v_mfma_f32_32x32x16_bf16 v[0:15], v[166:169], v[174:177], v[0:15]
	v_mfma_f32_32x32x16_bf16 v[16:31], v[148:151], v[198:201], v[16:31]
	v_mfma_f32_32x32x16_bf16 v[16:31], v[166:169], v[202:205], v[16:31]
	global_load_dwordx4 v[148:151], v[240:241], off offset:640
	global_load_dwordx4 v[166:169], v[242:243], off offset:640
	global_load_dwordx4 v[170:173], v[248:249], off offset:640
	global_load_dwordx4 v[174:177], v[250:251], off offset:640
	global_load_dwordx4 v[198:201], v[252:253], off offset:640
	global_load_dwordx4 v[202:205], v[254:255], off offset:640
	s_waitcnt vmcnt(18)
	ds_write_b128 v194, v[216:219]
	ds_write_b128 v194, v[220:223] offset:1024
	ds_write_b128 v194, v[224:227] offset:2048
	ds_write_b128 v194, v[228:231] offset:3072
	ds_write_b128 v194, v[232:235] offset:4096
	ds_write_b128 v194, v[236:239] offset:5120
	ds_read_b128 v[216:219], v244
	ds_read_b128 v[220:223], v245
	ds_read_b128 v[224:227], v244 offset:2048
	ds_read_b128 v[228:231], v245 offset:2048
	ds_read_b128 v[232:235], v244 offset:4096
	ds_read_b128 v[236:239], v245 offset:4096
	s_waitcnt lgkmcnt(0)
	v_mfma_f32_32x32x16_bf16 v[0:15], v[216:219], v[224:227], v[0:15]
	v_mfma_f32_32x32x16_bf16 v[0:15], v[220:223], v[228:231], v[0:15]
	v_mfma_f32_32x32x16_bf16 v[16:31], v[216:219], v[232:235], v[16:31]
	v_mfma_f32_32x32x16_bf16 v[16:31], v[220:223], v[236:239], v[16:31]
	s_waitcnt vmcnt(12)
	ds_write_b128 v194, v[82:85]
	ds_write_b128 v194, v[86:89] offset:1024
	ds_write_b128 v194, v[90:93] offset:2048
	ds_write_b128 v194, v[94:97] offset:3072
	ds_write_b128 v194, v[98:101] offset:4096
	ds_write_b128 v194, v[102:105] offset:5120
	ds_read_b128 v[82:85], v244
	ds_read_b128 v[86:89], v245
	ds_read_b128 v[90:93], v244 offset:2048
	ds_read_b128 v[94:97], v245 offset:2048
	ds_read_b128 v[98:101], v244 offset:4096
	ds_read_b128 v[102:105], v245 offset:4096
	s_waitcnt lgkmcnt(0)
	v_mfma_f32_32x32x16_bf16 v[0:15], v[82:85], v[90:93], v[0:15]
	v_mfma_f32_32x32x16_bf16 v[0:15], v[86:89], v[94:97], v[0:15]
	v_mfma_f32_32x32x16_bf16 v[16:31], v[82:85], v[98:101], v[16:31]
	v_mfma_f32_32x32x16_bf16 v[16:31], v[86:89], v[102:105], v[16:31]
	s_waitcnt vmcnt(6)
	ds_write_b128 v194, v[106:109]
	ds_write_b128 v194, v[110:113] offset:1024
	ds_write_b128 v194, v[132:135] offset:2048
	ds_write_b128 v194, v[136:139] offset:3072
	ds_write_b128 v194, v[140:143] offset:4096
	ds_write_b128 v194, v[144:147] offset:5120
	ds_read_b128 v[106:109], v244
	ds_read_b128 v[110:113], v245
	ds_read_b128 v[132:135], v244 offset:2048
	ds_read_b128 v[136:139], v245 offset:2048
	ds_read_b128 v[140:143], v244 offset:4096
	ds_read_b128 v[144:147], v245 offset:4096
	s_waitcnt lgkmcnt(0)
	v_mfma_f32_32x32x16_bf16 v[0:15], v[106:109], v[132:135], v[0:15]
	v_mfma_f32_32x32x16_bf16 v[0:15], v[110:113], v[136:139], v[0:15]
	v_mfma_f32_32x32x16_bf16 v[16:31], v[106:109], v[140:143], v[16:31]
	v_mfma_f32_32x32x16_bf16 v[16:31], v[110:113], v[144:147], v[16:31]
	s_waitcnt vmcnt(0)
	ds_write_b128 v194, v[148:151]
	ds_write_b128 v194, v[166:169] offset:1024
	ds_write_b128 v194, v[170:173] offset:2048
	ds_write_b128 v194, v[174:177] offset:3072
	ds_write_b128 v194, v[198:201] offset:4096
	ds_write_b128 v194, v[202:205] offset:5120
	ds_read_b128 v[148:151], v244
	ds_read_b128 v[166:169], v245
	ds_read_b128 v[170:173], v244 offset:2048
	ds_read_b128 v[174:177], v245 offset:2048
	ds_read_b128 v[198:201], v244 offset:4096
	ds_read_b128 v[202:205], v245 offset:4096
	s_waitcnt lgkmcnt(0)
	v_mfma_f32_32x32x16_bf16 v[0:15], v[148:151], v[170:173], v[0:15]
	v_mfma_f32_32x32x16_bf16 v[0:15], v[166:169], v[174:177], v[0:15]
	v_mfma_f32_32x32x16_bf16 v[16:31], v[148:151], v[198:201], v[16:31]
	v_mfma_f32_32x32x16_bf16 v[16:31], v[166:169], v[202:205], v[16:31]
	s_barrier
	s_nop 11
	ds_write2_b32 v39, v0, v16 offset1:32
	ds_write2_b32 v39, v1, v17 offset0:64 offset1:96
	ds_write2_b32 v39, v2, v18 offset0:128 offset1:160
	ds_write2_b32 v39, v3, v19 offset0:192 offset1:224
	ds_write2_b32 v43, v4, v20 offset1:32
	ds_write2_b32 v43, v5, v21 offset0:64 offset1:96
	ds_write2_b32 v43, v6, v22 offset0:128 offset1:160
	ds_write2_b32 v43, v7, v23 offset0:192 offset1:224
	ds_write2_b32 v44, v8, v24 offset1:32
	ds_write2_b32 v44, v9, v25 offset0:64 offset1:96
	ds_write2_b32 v44, v10, v26 offset0:128 offset1:160
	ds_write2_b32 v44, v11, v27 offset0:192 offset1:224
	ds_write2_b32 v45, v12, v28 offset1:32
	ds_write2_b32 v45, v13, v29 offset0:64 offset1:96
	ds_write2_b32 v45, v14, v30 offset0:128 offset1:160
	ds_write2_b32 v45, v15, v31 offset0:192 offset1:224
	s_waitcnt lgkmcnt(0)
	s_barrier
	global_load_dwordx2 v[46:47], v[50:51], off
	v_lshl_add_u64 v[0:1], s[74:75], 0, v[32:33]
	v_lshl_add_u64 v[48:49], v[58:59], 2, v[0:1]
	ds_read_b128 v[0:3], v42
	ds_read_b128 v[4:7], v42 offset:8192
	ds_read_b128 v[8:11], v42 offset:16384
	ds_read_b128 v[12:15], v42 offset:24576
	ds_read_b128 v[16:19], v42 offset:32768
	ds_read_b128 v[20:23], v42 offset:40960
	ds_read_b128 v[24:27], v42 offset:49152
	ds_read_b128 v[28:31], v42 offset:57344
	s_waitcnt lgkmcnt(7)
	v_pk_add_f32 v[2:3], v[2:3], 0 op_sel_hi:[1,0]
	v_pk_add_f32 v[0:1], v[0:1], 0 op_sel_hi:[1,0]
	s_waitcnt lgkmcnt(6)
	v_pk_add_f32 v[2:3], v[2:3], v[6:7]
	v_pk_add_f32 v[0:1], v[0:1], v[4:5]
	s_waitcnt lgkmcnt(5)
	v_pk_add_f32 v[2:3], v[2:3], v[10:11]
	v_pk_add_f32 v[0:1], v[0:1], v[8:9]
	s_waitcnt lgkmcnt(4)
	v_pk_add_f32 v[2:3], v[2:3], v[14:15]
	v_pk_add_f32 v[0:1], v[0:1], v[12:13]
	s_waitcnt lgkmcnt(3)
	v_pk_add_f32 v[2:3], v[2:3], v[18:19]
	v_pk_add_f32 v[0:1], v[0:1], v[16:17]
	s_waitcnt lgkmcnt(2)
	v_pk_add_f32 v[2:3], v[2:3], v[22:23]
	v_pk_add_f32 v[0:1], v[0:1], v[20:21]
	s_waitcnt lgkmcnt(1)
	v_pk_add_f32 v[2:3], v[2:3], v[26:27]
	v_pk_add_f32 v[0:1], v[0:1], v[24:25]
	s_waitcnt lgkmcnt(0)
	v_pk_add_f32 v[2:3], v[2:3], v[30:31]
	v_pk_add_f32 v[0:1], v[0:1], v[28:29]
	s_waitcnt vmcnt(0)
	v_lshlrev_b32_e32 v4, 16, v46
	v_and_b32_e32 v5, 0xffff0000, v46
	v_lshlrev_b32_e32 v6, 16, v47
	v_and_b32_e32 v7, 0xffff0000, v47
	v_pk_add_f32 v[0:1], v[0:1], v[4:5]
	v_pk_add_f32 v[2:3], v[2:3], v[6:7]
	global_store_dwordx4 v[48:49], v[0:3], off
	s_cbranch_scc1 .LBB0_1522

; __global__ void __launch_bounds__(512, 2) fwd_kernel(Params p) {
	.amdhsa_kernel _Z10fwd_kernel6Params
		.amdhsa_group_segment_fixed_size 0
		.amdhsa_private_segment_fixed_size 0
		.amdhsa_kernarg_size 496
		.amdhsa_user_sgpr_count 2
		.amdhsa_user_sgpr_dispatch_ptr 0
		.amdhsa_user_sgpr_queue_ptr 0
		.amdhsa_user_sgpr_kernarg_segment_ptr 1
		.amdhsa_user_sgpr_dispatch_id 0
		.amdhsa_user_sgpr_kernarg_preload_length 0
		.amdhsa_user_sgpr_kernarg_preload_offset 0
		.amdhsa_user_sgpr_private_segment_size 0
		.amdhsa_uses_dynamic_stack 0
		.amdhsa_enable_private_segment 0
		.amdhsa_system_sgpr_workgroup_id_x 1
		.amdhsa_system_sgpr_workgroup_id_y 0
		.amdhsa_system_sgpr_workgroup_id_z 0
		.amdhsa_system_sgpr_workgroup_info 0
		.amdhsa_system_vgpr_workitem_id 2
		.amdhsa_next_free_vgpr 256
		.amdhsa_next_free_sgpr 98
		.amdhsa_accum_offset 256
		.amdhsa_reserve_vcc 1
		.amdhsa_float_round_mode_32 0
		.amdhsa_float_round_mode_16_64 0
		.amdhsa_float_denorm_mode_32 3
		.amdhsa_float_denorm_mode_16_64 3
		.amdhsa_dx10_clamp 1
		.amdhsa_ieee_mode 1
		.amdhsa_fp16_overflow 0
		.amdhsa_tg_split 0
		.amdhsa_exception_fp_ieee_invalid_op 0
		.amdhsa_exception_fp_denorm_src 0
		.amdhsa_exception_fp_ieee_div_zero 0
		.amdhsa_exception_fp_ieee_overflow 0
		.amdhsa_exception_fp_ieee_underflow 0
		.amdhsa_exception_fp_ieee_inexact 0
		.amdhsa_exception_int_div_zero 0
	.end_amdhsa_kernel

; __global__ void __launch_bounds__(512, 2) fwd_kernel(Params p) {
amdhsa.kernels:
  - .agpr_count:     0
    .args:
      - .offset:         0
        .size:           240
        .value_kind:     by_value
      - .offset:         240
        .size:           4
        .value_kind:     hidden_block_count_x
      - .offset:         244
        .size:           4
        .value_kind:     hidden_block_count_y
      - .offset:         248
        .size:           4
        .value_kind:     hidden_block_count_z
      - .offset:         252
        .size:           2
        .value_kind:     hidden_group_size_x
      - .offset:         254
        .size:           2
        .value_kind:     hidden_group_size_y
      - .offset:         256
        .size:           2
        .value_kind:     hidden_group_size_z
      - .offset:         258
        .size:           2
        .value_kind:     hidden_remainder_x
      - .offset:         260
        .size:           2
        .value_kind:     hidden_remainder_y
      - .offset:         262
        .size:           2
        .value_kind:     hidden_remainder_z
      - .offset:         280
        .size:           8
        .value_kind:     hidden_global_offset_x
      - .offset:         288
        .size:           8
        .value_kind:     hidden_global_offset_y
      - .offset:         296
        .size:           8
        .value_kind:     hidden_global_offset_z
      - .offset:         304
        .size:           2
        .value_kind:     hidden_grid_dims
      - .offset:         328
        .size:           8
        .value_kind:     hidden_multigrid_sync_arg
      - .offset:         360
        .size:           4
        .value_kind:     hidden_dynamic_lds_size
    .group_segment_fixed_size: 0
    .kernarg_segment_align: 8
    .kernarg_segment_size: 496
    .language:       OpenCL C
    .language_version:
      - 2
      - 0
    .max_flat_workgroup_size: 512
    .name:           _Z10fwd_kernel6Params
    .private_segment_fixed_size: 0
    .sgpr_count:     104
    .sgpr_spill_count: 28
    .symbol:         _Z10fwd_kernel6Params.kd
    .uniform_work_group_size: 1
    .uses_dynamic_stack: false
    .vgpr_count:     256
    .vgpr_spill_count: 0
    .wavefront_size: 64
